# speedup vs baseline: 1.0591x; 1.0012x over previous
; __device__ __forceinline__ void ssm3_item(KP p, int layer, int b, int c, char* smem, int tix) {
;     ...
;       for (int j0 = c - 1; j0 >= 0; j0 -= 16) {
;         float2 xv[16];
; #pragma unroll
;         for (int u = 0; u < 16; ++u) {
;           const int j = j0 - u;
;           xv[u] = (j >= 0) ? xlb[(size_t)j * 2048] : make_float2(0.f, 0.f);
;         }
; #pragma unroll
;         for (int u = 0; u < 16; ++u) {
;           xr += pr * xv[u].x - pi * xv[u].y;
;           xi += pr * xv[u].y + pi * xv[u].x;
;           float npr = pr * a64r - pi * a64i, npi = pr * a64i + pi * a64r;
;           pr = npr; pi = npi;
;         }
.LBB0_285:
	global_load_dwordx2 v[94:95], v[88:89], off
	v_add_u32_e32 v77, 15, v90
	v_cmp_lt_i32_e32 vcc, 14, v77
	s_cbranch_vccz .Lcarry_slow
	s_mov_b32 s14, 0xffffc000
	s_mov_b32 s15, -1
	v_lshl_add_u64 v[144:145], v[88:89], 0, s[14:15]
	global_load_dwordx2 v[92:93], v[144:145], off
	v_lshl_add_u64 v[144:145], v[144:145], 0, s[14:15]
	global_load_dwordx2 v[100:101], v[144:145], off
	v_lshl_add_u64 v[144:145], v[144:145], 0, s[14:15]
	global_load_dwordx2 v[96:97], v[144:145], off
	v_lshl_add_u64 v[144:145], v[144:145], 0, s[14:15]
	global_load_dwordx2 v[106:107], v[144:145], off
	v_lshl_add_u64 v[144:145], v[144:145], 0, s[14:15]
	global_load_dwordx2 v[102:103], v[144:145], off
	v_lshl_add_u64 v[144:145], v[144:145], 0, s[14:15]
	global_load_dwordx2 v[110:111], v[144:145], off
	v_lshl_add_u64 v[144:145], v[144:145], 0, s[14:15]
	global_load_dwordx2 v[98:99], v[144:145], off
	v_lshl_add_u64 v[144:145], v[144:145], 0, s[14:15]
	global_load_dwordx2 v[108:109], v[144:145], off
	v_lshl_add_u64 v[144:145], v[144:145], 0, s[14:15]
	global_load_dwordx2 v[104:105], v[144:145], off
	v_lshl_add_u64 v[144:145], v[144:145], 0, s[14:15]
	global_load_dwordx2 v[114:115], v[144:145], off
	v_lshl_add_u64 v[144:145], v[144:145], 0, s[14:15]
	global_load_dwordx2 v[112:113], v[144:145], off
	v_lshl_add_u64 v[144:145], v[144:145], 0, s[14:15]
	global_load_dwordx2 v[118:119], v[144:145], off
	v_lshl_add_u64 v[144:145], v[144:145], 0, s[14:15]
	global_load_dwordx2 v[116:117], v[144:145], off
	v_lshl_add_u64 v[144:145], v[144:145], 0, s[14:15]
	global_load_dwordx2 v[122:123], v[144:145], off
	v_lshl_add_u64 v[144:145], v[144:145], 0, s[14:15]
	global_load_dwordx2 v[120:121], v[144:145], off
	s_branch .LBB0_284
.Lcarry_slow:
	v_cmp_lt_i32_e32 vcc, 0, v77
	v_mov_b32_e32 v92, 0
	v_mov_b32_e32 v93, 0
	s_and_saveexec_b64 s[14:15], vcc
	s_cbranch_execz .LBB0_287
	v_add_u32_e32 v0, 14, v90
	v_lshlrev_b64 v[92:93], 14, v[0:1]
	v_lshl_add_u64 v[92:93], v[84:85], 0, v[92:93]
	global_load_dwordx2 v[92:93], v[92:93], off
